# same as previous but at most 1 conversion chunk per wave in the idle gate/up round
# speedup vs baseline: 1.0057x; 1.0057x over previous
; #define ARG_WS() ((unsigned char*)karg64(8 * 19))
; #define REP(k) for (int rep_ = 0; rep_ < (DUP_PHASE == (k) ? 2 : 1); ++rep_, (DUP_PHASE == (k) ? xcd_barrier(bar) : (void)0))
; #define IDX() int tid = threadIdx.x, bid = blockIdx.x, G = gridDim.x; asm volatile("" : "+v"(tid)); asm volatile("" : "+s"(bid), "+s"(G)); \
;     const int lane = tid & 63, wave = __builtin_amdgcn_readfirstlane(tid >> 6), gw = bid * NWAVES + wave, NGW = G * NWAVES; (void)lane; (void)gw; (void)NGW; (void)wave
; #define SEAM(k) do { if (N_LAUNCH_MODE == 0 && IN(k) && IN((k) + 1)) xcd_barrier(bar); } while (0)
; template <int PHM, int ATTM> __global__ void __launch_bounds__(NWAVES * 64, 2) fwd_kernel(Args args) {
;     ...
;         REP(8) if (IN(pb + 7) && EN(8)) { IDX(); unsigned char* ws = ARG_WS();
;             pg8::Gemm g{WSP(bf16, WS_U), WSP(bf16, WS_W + (size_t)layer * W_LAYER + W_GU), M, NGU, DM}; pg8::StaticOrder S; S.init(M, NGU, G, bid);
;             pg8::EpiSwiglu E{WSP(bf16, WS_ACT), DFF}; pg8::gemm_phase<pg8::EpiSwiglu, pg8::StaticOrder, true, true>(lds, g, S, E); }
;         SEAM(pb + 7);
.LBB0_2171:
	s_waitcnt vmcnt(0)
	s_barrier
	v_readlane_b32 s4, v255, 21
	s_cmp_gt_u32 s4, 1
	s_cbranch_scc1 .Lmy_ec_skip
	s_cmp_lt_u32 s66, 0x80
	s_cbranch_scc1 .Lmy_ec_skip
	v_writelane_b32 v255, s2, 32
	v_writelane_b32 v255, s3, 33
	s_add_i32 s4, s4, 1
	v_writelane_b32 v255, s4, 21
	s_mul_i32 s64, s4, 40
	v_readfirstlane_b32 s5, v0
	s_lshr_b32 s5, s5, 6
	s_lshl_b32 s46, s5, 14
	v_cmp_eq_u32_e64 s[38:39], 0, v239
	s_mov_b32 s99, 1
	s_mov_b32 s98, 2
	s_nop 3
	s_branch .Lmy_ec_entry
